# GEMM K-loop static priority raise moved to the leading wave half (waves 0-3) instead of the trailing half
# speedup vs baseline: 1.0025x; 1.0014x over previous
; template <class Epi, class Sched, bool ALIGN_EPI = false, bool SP2 = false>
; __device__ __forceinline__ void gemm_phase(PG8_LAS unsigned char* lds, const Gemm g, const Sched& S, const Epi& E) {
;     ...
; #pragma unroll
;         for (int a = 0; a < 2; ++a)
; #pragma unroll
;             for (int b = 0; b < 2; ++b)
; #pragma unroll
;                 for (int m = 0; m < 4; ++m)
; #pragma unroll
;                     for (int n = 0; n < 2; ++n) acc[a][b][m][n] = (f32x4){0.f, 0.f, 0.f, 0.f};
;         cur = nxt; cA = nA; cB = nB; ++ui;
.LBB0_185:
	s_add_u32 s12, s12, 0x80
	s_addc_u32 s13, s13, 0
	s_add_u32 s16, s14, 0x100
	v_mov_b32_e32 v0, 0
	s_addc_u32 s17, s15, 0
	s_mov_b32 s0, 0
	v_mov_b32_e32 v1, v0
	v_mov_b32_e32 v2, v0
	v_mov_b32_e32 v3, v0
	v_mov_b32_e32 v4, v0
	v_mov_b32_e32 v5, v0
	v_mov_b32_e32 v6, v0
	v_mov_b32_e32 v7, v0
	v_mov_b32_e32 v8, v0
	v_mov_b32_e32 v9, v0
	v_mov_b32_e32 v10, v0
	v_mov_b32_e32 v11, v0
	v_mov_b32_e32 v16, v0
	v_mov_b32_e32 v17, v0
	v_mov_b32_e32 v18, v0
	v_mov_b32_e32 v19, v0
	v_mov_b32_e32 v24, v0
	v_mov_b32_e32 v25, v0
	v_mov_b32_e32 v26, v0
	v_mov_b32_e32 v27, v0
	v_mov_b32_e32 v32, v0
	v_mov_b32_e32 v33, v0
	v_mov_b32_e32 v34, v0
	v_mov_b32_e32 v35, v0
	v_mov_b32_e32 v40, v0
	v_mov_b32_e32 v41, v0
	v_mov_b32_e32 v42, v0
	v_mov_b32_e32 v43, v0
	v_mov_b32_e32 v48, v0
	v_mov_b32_e32 v49, v0
	v_mov_b32_e32 v50, v0
	v_mov_b32_e32 v51, v0
	v_mov_b32_e32 v12, v0
	v_mov_b32_e32 v13, v0
	v_mov_b32_e32 v14, v0
	v_mov_b32_e32 v15, v0
	v_mov_b32_e32 v20, v0
	v_mov_b32_e32 v21, v0
	v_mov_b32_e32 v22, v0
	v_mov_b32_e32 v23, v0
	v_mov_b32_e32 v28, v0
	v_mov_b32_e32 v29, v0
	v_mov_b32_e32 v30, v0
	v_mov_b32_e32 v31, v0
	v_mov_b32_e32 v36, v0
	v_mov_b32_e32 v37, v0
	v_mov_b32_e32 v38, v0
	v_mov_b32_e32 v39, v0
	v_mov_b32_e32 v44, v0
	v_mov_b32_e32 v45, v0
	v_mov_b32_e32 v46, v0
	v_mov_b32_e32 v47, v0
	v_mov_b32_e32 v52, v0
	v_mov_b32_e32 v53, v0
	v_mov_b32_e32 v54, v0
	v_mov_b32_e32 v55, v0
	v_mov_b32_e32 v56, v0
	v_mov_b32_e32 v57, v0
	v_mov_b32_e32 v58, v0
	v_mov_b32_e32 v59, v0
	v_mov_b32_e32 v60, v0
	v_mov_b32_e32 v61, v0
	v_mov_b32_e32 v62, v0
	v_mov_b32_e32 v63, v0
	v_mov_b32_e32 v64, v0
	v_mov_b32_e32 v65, v0
	v_mov_b32_e32 v66, v0
	v_mov_b32_e32 v67, v0
	v_mov_b32_e32 v68, v0
	v_mov_b32_e32 v69, v0
	v_mov_b32_e32 v70, v0
	v_mov_b32_e32 v71, v0
	v_mov_b32_e32 v72, v0
	v_mov_b32_e32 v73, v0
	v_mov_b32_e32 v74, v0
	v_mov_b32_e32 v75, v0
	v_mov_b32_e32 v76, v0
	v_mov_b32_e32 v77, v0
	v_mov_b32_e32 v78, v0
	v_mov_b32_e32 v79, v0
	v_mov_b32_e32 v88, v0
	v_mov_b32_e32 v89, v0
	v_mov_b32_e32 v90, v0
	v_mov_b32_e32 v91, v0
	v_mov_b32_e32 v92, v0
	v_mov_b32_e32 v93, v0
	v_mov_b32_e32 v94, v0
	v_mov_b32_e32 v95, v0
	v_mov_b32_e32 v104, v0
	v_mov_b32_e32 v105, v0
	v_mov_b32_e32 v106, v0
	v_mov_b32_e32 v107, v0
	v_mov_b32_e32 v108, v0
	v_mov_b32_e32 v109, v0
	v_mov_b32_e32 v110, v0
	v_mov_b32_e32 v111, v0
	v_mov_b32_e32 v80, v0
	v_mov_b32_e32 v81, v0
	v_mov_b32_e32 v82, v0
	v_mov_b32_e32 v83, v0
	v_mov_b32_e32 v84, v0
	v_mov_b32_e32 v85, v0
	v_mov_b32_e32 v86, v0
	v_mov_b32_e32 v87, v0
	v_mov_b32_e32 v96, v0
	v_mov_b32_e32 v97, v0
	v_mov_b32_e32 v98, v0
	v_mov_b32_e32 v99, v0
	v_mov_b32_e32 v100, v0
	v_mov_b32_e32 v101, v0
	v_mov_b32_e32 v102, v0
	v_mov_b32_e32 v103, v0
	v_mov_b32_e32 v112, v0
	v_mov_b32_e32 v113, v0
	v_mov_b32_e32 v114, v0
	v_mov_b32_e32 v115, v0
	v_mov_b32_e32 v116, v0
	v_mov_b32_e32 v117, v0
	v_mov_b32_e32 v118, v0
	v_mov_b32_e32 v119, v0
	v_mov_b32_e32 v120, v0
	v_mov_b32_e32 v121, v0
	v_mov_b32_e32 v122, v0
	v_mov_b32_e32 v123, v0
	v_mov_b32_e32 v124, v0
	v_mov_b32_e32 v125, v0
	v_mov_b32_e32 v126, v0
	v_mov_b32_e32 v127, v0
	s_and_b64 vcc, exec, s[92:93]
	s_cbranch_vccz .Lgemm_prio_skip
	s_setprio 1
